# attention: V-fragment LDS reads prefetched two MFMA pairs ahead into dedicated registers (on top of v7)
# baseline (speedup 1.0000x reference)
.Latt_prio_done:
.LBB0_674:
	s_add_i32 s2, s67, -1
	s_and_b32 s2, s2, 3
	s_mulk_i32 s2, 0x3400
	s_and_b32 s71, s67, 2
	s_add_i32 s2, s2, 0
	s_xor_b32 s3, s71, 2
	v_add_u32_e32 v0, s2, v192
	s_mulk_i32 s3, 0x2400
	s_waitcnt vmcnt(5)
	ds_write_b128 v0, v[152:155]
	v_add_u32_e32 v0, s2, v185
	s_add_i32 s2, s67, 5
	s_waitcnt vmcnt(4)
	ds_write_b128 v0, v[156:159] offset:128
	v_add_u32_e32 v0, s3, v193
	s_min_i32 s46, s2, s66
	s_add_i32 s2, s67, 4
	v_add_u32_e32 v0, 0xd000, v0
	s_min_i32 s2, s2, s66
	s_lshl_b64 s[4:5], s[46:47], 16
	s_mov_b32 s3, s47
	s_waitcnt vmcnt(3)
	ds_write2_b64 v0, v[172:173], v[174:175] offset1:2
	v_lshl_add_u64 v[2:3], v[186:187], 0, s[4:5]
	s_lshl_b64 s[4:5], s[46:47], 12
	s_lshl_b64 s[2:3], s[2:3], 7
	v_lshl_add_u64 v[4:5], v[188:189], 0, s[4:5]
	global_load_dwordx4 v[152:155], v[2:3], off
	global_load_dwordx4 v[156:159], v[4:5], off
	v_lshl_add_u64 v[2:3], v[190:191], 0, s[2:3]
	global_load_dwordx4 v[172:175], v[2:3], off
	s_add_i32 s70, s67, 1
	s_and_b32 s69, s70, 3
	s_cmp_gt_i32 s67, s65
	s_cbranch_scc1 .LBB0_685
	s_mul_i32 s2, s69, 0x3400
	v_add_u32_e32 v0, s2, v196
	ds_read_b128 v[2:5], v0
	ds_read_b128 v[6:9], v0 offset:6656
	s_waitcnt lgkmcnt(1)
	v_mfma_f32_32x32x16_bf16 v[112:127], v[2:5], v[128:131], v[48:63]
	ds_read_b128 v[10:13], v0 offset:32
	ds_read_b128 v[202:205], v0 offset:6688
	v_add_f32_e32 v14, 0, v80
	v_add_f32_e32 v14, v81, v14
	v_cvt_pk_bf16_f32 v176, v80, v81
	s_waitcnt lgkmcnt(2)
	v_mfma_f32_32x32x16_bf16 v[96:111], v[6:9], v[128:131], v[48:63]
	v_add_f32_e32 v2, v82, v14
	v_add_f32_e32 v2, v83, v2
	v_add_f32_e32 v14, v84, v2
	v_cvt_pk_bf16_f32 v177, v82, v83
	s_waitcnt lgkmcnt(1)
	v_mfma_f32_32x32x16_bf16 v[112:127], v[10:13], v[132:135], v[112:127]
	ds_read_b128 v[2:5], v0 offset:64
	ds_read_b128 v[6:9], v0 offset:6720
	v_add_f32_e32 v14, v85, v14
	v_add_f32_e32 v14, v86, v14
	v_add_f32_e32 v14, v87, v14
	v_cvt_pk_bf16_f32 v178, v84, v85
	v_cvt_pk_bf16_f32 v179, v86, v87
	s_waitcnt lgkmcnt(2)
	v_mfma_f32_32x32x16_bf16 v[96:111], v[202:205], v[132:135], v[96:111]
	v_add_f32_e32 v10, v88, v14
	v_add_f32_e32 v11, v89, v10
	v_cvt_pk_bf16_f32 v10, v88, v89
	s_waitcnt lgkmcnt(1)
	v_mfma_f32_32x32x16_bf16 v[112:127], v[2:5], v[136:139], v[112:127]
	ds_read_b128 v[80:83], v0 offset:96
	ds_read_b128 v[202:205], v0 offset:6752
	v_add_f32_e32 v11, v90, v11
	v_add_f32_e32 v11, v91, v11
	v_add_f32_e32 v12, v92, v11
	v_cvt_pk_bf16_f32 v11, v90, v91
	s_waitcnt lgkmcnt(2)
	v_mfma_f32_32x32x16_bf16 v[96:111], v[6:9], v[136:139], v[96:111]
	v_add_f32_e32 v2, v93, v12
	v_add_f32_e32 v2, v94, v2
	v_add_f32_e32 v14, v95, v2
	v_cvt_pk_bf16_f32 v12, v92, v93
	v_cvt_pk_bf16_f32 v13, v94, v95
	s_waitcnt lgkmcnt(1)
	v_mfma_f32_32x32x16_bf16 v[112:127], v[80:83], v[140:143], v[112:127]
	ds_read_b128 v[2:5], v0 offset:128
	ds_read_b128 v[206:209], v0 offset:6784
	v_add_f32_e32 v6, v16, v14
	v_add_f32_e32 v7, v17, v6
	v_cvt_pk_bf16_f32 v6, v16, v17
	s_waitcnt lgkmcnt(2)
	v_mfma_f32_32x32x16_bf16 v[96:111], v[202:205], v[140:143], v[96:111]
	v_add_f32_e32 v7, v18, v7
	v_add_f32_e32 v7, v19, v7
	v_add_f32_e32 v8, v20, v7
	v_cvt_pk_bf16_f32 v7, v18, v19
	s_waitcnt lgkmcnt(1)
	v_mfma_f32_32x32x16_bf16 v[112:127], v[2:5], v[144:147], v[112:127]
	ds_read_b128 v[14:17], v0 offset:160
	ds_read_b128 v[80:83], v0 offset:6816
	v_add_f32_e32 v0, v21, v8
	v_add_f32_e32 v0, v22, v0
	v_add_f32_e32 v0, v23, v0
	v_cvt_pk_bf16_f32 v8, v20, v21
	v_cvt_pk_bf16_f32 v9, v22, v23
	s_waitcnt lgkmcnt(2)
	v_mfma_f32_32x32x16_bf16 v[96:111], v[206:209], v[144:147], v[96:111]
	v_add_f32_e32 v0, v24, v0
	v_add_f32_e32 v0, v25, v0
	v_cvt_pk_bf16_f32 v2, v24, v25
	s_waitcnt lgkmcnt(1)
	v_mfma_f32_32x32x16_bf16 v[112:127], v[14:17], v[148:151], v[112:127]
	v_add_f32_e32 v0, v26, v0
	v_add_f32_e32 v0, v27, v0
	v_add_f32_e32 v0, v28, v0
	v_cvt_pk_bf16_f32 v3, v26, v27
	s_waitcnt lgkmcnt(0)
	v_mfma_f32_32x32x16_bf16 v[96:111], v[80:83], v[148:151], v[96:111]
	v_add_f32_e32 v0, v29, v0
	v_add_f32_e32 v0, v30, v0
	v_add_f32_e32 v0, v31, v0
	v_cvt_pk_bf16_f32 v4, v28, v29
	v_cvt_pk_bf16_f32 v5, v30, v31
	s_mul_i32 s4, s71, 0x2400
	v_add_u32_e32 v206, s4, v200
	ds_read_b128 v[16:19], v206 offset:53248
	ds_read_b128 v[202:205], v206 offset:57856
	ds_read_b128 v[210:213], v206 offset:53280
	ds_read_b128 v[214:217], v206 offset:57888
	s_cmp_ge_i32 s67, s65
	v_add_f32_e32 v201, v201, v0
	s_cbranch_scc1 .LBB0_682
	s_sub_i32 s2, s68, 64
	s_cmp_le_i32 s2, s63
	s_cbranch_scc1 .LBB0_680
	v_add_u32_e32 v0, s68, v197
	v_add_u32_e32 v15, 0xffffffa1, v0
	v_add_u32_e32 v14, 0xffffff81, v0
	v_cmp_le_i32_e64 s[2:3], v15, v184
	v_cmp_le_i32_e32 vcc, v14, v184
	s_nop 0
	v_cndmask_b32_e64 v96, v194, v96, s[2:3]
	v_cmp_lt_i32_e64 s[2:3], v14, v184
	v_add_u32_e32 v14, 0xffffffa2, v0
	v_cmp_le_i32_e64 s[4:5], v14, v184
	v_add_u32_e32 v14, 0xffffff83, v0
	s_nop 0
	v_cndmask_b32_e64 v97, v194, v97, s[4:5]
	v_cmp_le_i32_e64 s[4:5], v14, v184
	v_add_u32_e32 v14, 0xffffffa3, v0
	v_cmp_le_i32_e64 s[6:7], v14, v184
	v_add_u32_e32 v14, 0xffffff84, v0
	s_nop 0
	v_cndmask_b32_e64 v98, v194, v98, s[6:7]
	v_cmp_le_i32_e64 s[6:7], v14, v184
	v_add_u32_e32 v14, 0xffffffa4, v0
	v_cmp_le_i32_e64 s[8:9], v14, v184
	v_add_u32_e32 v14, 0xffffff89, v0
	s_nop 0
	v_cndmask_b32_e64 v99, v194, v99, s[8:9]
	v_cmp_le_i32_e64 s[8:9], v14, v184
	v_add_u32_e32 v14, 0xffffffa9, v0
	v_cmp_le_i32_e64 s[10:11], v14, v184
	v_add_u32_e32 v14, 0xffffff8a, v0
	s_nop 0
	v_cndmask_b32_e64 v100, v194, v100, s[10:11]
	v_cmp_le_i32_e64 s[10:11], v14, v184
	v_add_u32_e32 v14, 0xffffffaa, v0
	v_cmp_le_i32_e64 s[12:13], v14, v184
	v_add_u32_e32 v14, 0xffffff8b, v0
	s_nop 0
	v_cndmask_b32_e64 v101, v194, v101, s[12:13]
	v_cmp_le_i32_e64 s[12:13], v14, v184
	v_add_u32_e32 v14, 0xffffffab, v0
	v_cmp_le_i32_e64 s[14:15], v14, v184
	v_add_u32_e32 v14, 0xffffff8c, v0
	s_nop 0
	v_cndmask_b32_e64 v102, v194, v102, s[14:15]
	v_cmp_le_i32_e64 s[14:15], v14, v184
	v_add_u32_e32 v14, 0xffffffac, v0
	v_cmp_le_i32_e64 s[16:17], v14, v184
	v_add_u32_e32 v14, 0xffffff91, v0
	s_nop 0
	v_cndmask_b32_e64 v103, v194, v103, s[16:17]
	v_cmp_le_i32_e64 s[16:17], v14, v184
	v_add_u32_e32 v14, 0xffffffb1, v0
	v_cmp_le_i32_e64 s[18:19], v14, v184
	v_add_u32_e32 v14, 0xffffff92, v0
	s_nop 0
	v_cndmask_b32_e64 v104, v194, v104, s[18:19]
	v_cmp_le_i32_e64 s[18:19], v14, v184
	v_add_u32_e32 v14, 0xffffffb2, v0
	v_cmp_le_i32_e64 s[20:21], v14, v184
	v_add_u32_e32 v14, 0xffffff93, v0
	s_nop 0
	v_cndmask_b32_e64 v105, v194, v105, s[20:21]
	v_cmp_le_i32_e64 s[20:21], v14, v184
	v_add_u32_e32 v14, 0xffffffb3, v0
	v_cmp_le_i32_e64 s[22:23], v14, v184
	v_add_u32_e32 v14, 0xffffff94, v0
	s_nop 0
	v_cndmask_b32_e64 v106, v194, v106, s[22:23]
	v_cmp_le_i32_e64 s[22:23], v14, v184
	v_add_u32_e32 v14, 0xffffffb4, v0
	v_cmp_le_i32_e64 s[24:25], v14, v184
	v_add_u32_e32 v14, 0xffffff99, v0
	s_nop 0
	v_cndmask_b32_e64 v107, v194, v107, s[24:25]
	v_cmp_le_i32_e64 s[24:25], v14, v184
	v_add_u32_e32 v14, 0xffffffb9, v0
	v_cmp_le_i32_e64 s[26:27], v14, v184
	v_add_u32_e32 v14, 0xffffff9a, v0
	s_nop 0
	v_cndmask_b32_e64 v108, v194, v108, s[26:27]
	v_cmp_le_i32_e64 s[26:27], v14, v184
	v_add_u32_e32 v14, 0xffffffba, v0
	v_cmp_le_i32_e64 s[28:29], v14, v184
	v_add_u32_e32 v14, 0xffffff9b, v0
	s_nop 0
	v_cndmask_b32_e64 v109, v194, v109, s[28:29]
	v_cmp_le_i32_e64 s[28:29], v14, v184
	v_add_u32_e32 v14, 0xffffffbb, v0
	v_cmp_le_i32_e64 s[30:31], v14, v184
	v_add_u32_e32 v14, 0xffffff9c, v0
	v_add_u32_e32 v0, 0xffffffbc, v0
	v_cndmask_b32_e64 v110, v194, v110, s[30:31]
	v_cmp_le_i32_e64 s[30:31], v14, v184
	v_cmp_gt_i32_e64 s[34:35], v0, v184
	s_and_saveexec_b64 s[48:49], s[34:35]
	v_mov_b32_e32 v111, s59
	s_or_b64 exec, exec, s[48:49]
	v_cndmask_b32_e64 v113, v194, v113, s[2:3]
	v_cndmask_b32_e32 v112, v194, v112, vcc
	v_cndmask_b32_e64 v114, v194, v114, s[4:5]
	v_cndmask_b32_e64 v115, v194, v115, s[6:7]
	v_cndmask_b32_e64 v116, v194, v116, s[8:9]
	v_cndmask_b32_e64 v117, v194, v117, s[10:11]
	v_cndmask_b32_e64 v118, v194, v118, s[12:13]
	v_cndmask_b32_e64 v119, v194, v119, s[14:15]
	v_cndmask_b32_e64 v120, v194, v120, s[16:17]
	v_cndmask_b32_e64 v121, v194, v121, s[18:19]
	v_cndmask_b32_e64 v122, v194, v122, s[20:21]
	v_cndmask_b32_e64 v123, v194, v123, s[22:23]
	v_cndmask_b32_e64 v124, v194, v124, s[24:25]
	v_cndmask_b32_e64 v125, v194, v125, s[26:27]
	v_cndmask_b32_e64 v126, v194, v126, s[28:29]
	v_cndmask_b32_e64 v127, v194, v127, s[30:31]

.LBB0_683:
	s_waitcnt lgkmcnt(3)
	v_mfma_f32_32x32x16_bf16 v[64:79], v[16:19], v[176:179], v[64:79]
	ds_read_b128 v[218:221], v206 offset:53312
	v_exp_f32_e32 v80, v112
	v_exp_f32_e32 v81, v113
	v_exp_f32_e32 v82, v114
	v_exp_f32_e32 v83, v115
	s_waitcnt lgkmcnt(3)
	v_mfma_f32_32x32x16_bf16 v[32:47], v[202:205], v[176:179], v[32:47]
	ds_read_b128 v[222:225], v206 offset:57920
	v_exp_f32_e32 v84, v116
	v_exp_f32_e32 v85, v117
	v_exp_f32_e32 v86, v118
	v_exp_f32_e32 v87, v119
	s_waitcnt lgkmcnt(3)
	v_mfma_f32_32x32x16_bf16 v[64:79], v[210:213], v[10:13], v[64:79]
	ds_read_b128 v[226:229], v206 offset:53344
	v_exp_f32_e32 v88, v120
	v_exp_f32_e32 v89, v121
	v_exp_f32_e32 v90, v122
	v_exp_f32_e32 v91, v123
	s_waitcnt lgkmcnt(3)
	v_mfma_f32_32x32x16_bf16 v[32:47], v[214:217], v[10:13], v[32:47]
	ds_read_b128 v[230:233], v206 offset:57952
	v_exp_f32_e32 v92, v124
	v_exp_f32_e32 v93, v125
	v_exp_f32_e32 v94, v126
	v_exp_f32_e32 v95, v127
	s_waitcnt lgkmcnt(3)
	v_mfma_f32_32x32x16_bf16 v[64:79], v[218:221], v[6:9], v[64:79]
	v_exp_f32_e32 v16, v96
	v_exp_f32_e32 v17, v97
	v_exp_f32_e32 v18, v98
	v_exp_f32_e32 v19, v99
	s_waitcnt lgkmcnt(2)
	v_mfma_f32_32x32x16_bf16 v[32:47], v[222:225], v[6:9], v[32:47]
	v_exp_f32_e32 v20, v100
	v_exp_f32_e32 v21, v101
	v_exp_f32_e32 v22, v102
	v_exp_f32_e32 v23, v103
	s_waitcnt lgkmcnt(1)
	v_mfma_f32_32x32x16_bf16 v[64:79], v[226:229], v[2:5], v[64:79]
	v_exp_f32_e32 v24, v104
	v_exp_f32_e32 v25, v105
	v_exp_f32_e32 v26, v106
	v_exp_f32_e32 v27, v107
	s_waitcnt lgkmcnt(0)
	v_mfma_f32_32x32x16_bf16 v[32:47], v[230:233], v[2:5], v[32:47]
	v_exp_f32_e32 v28, v108
	v_exp_f32_e32 v29, v109
	v_exp_f32_e32 v30, v110
	v_exp_f32_e32 v31, v111
	s_andn2_b64 vcc, exec, s[2:3]
	s_cbranch_vccnz .LBB0_685
	v_pk_mul_f32 v[78:79], v[0:1], v[78:79] op_sel_hi:[0,1]
	v_pk_mul_f32 v[76:77], v[0:1], v[76:77] op_sel_hi:[0,1]
	v_pk_mul_f32 v[74:75], v[0:1], v[74:75] op_sel_hi:[0,1]
	v_pk_mul_f32 v[72:73], v[0:1], v[72:73] op_sel_hi:[0,1]
	v_pk_mul_f32 v[70:71], v[0:1], v[70:71] op_sel_hi:[0,1]
	v_pk_mul_f32 v[68:69], v[0:1], v[68:69] op_sel_hi:[0,1]
	v_pk_mul_f32 v[66:67], v[0:1], v[66:67] op_sel_hi:[0,1]
	v_pk_mul_f32 v[64:65], v[0:1], v[64:65] op_sel_hi:[0,1]
	v_pk_mul_f32 v[46:47], v[0:1], v[46:47] op_sel_hi:[0,1]
	v_pk_mul_f32 v[44:45], v[0:1], v[44:45] op_sel_hi:[0,1]
	v_pk_mul_f32 v[42:43], v[0:1], v[42:43] op_sel_hi:[0,1]
	v_pk_mul_f32 v[40:41], v[0:1], v[40:41] op_sel_hi:[0,1]
	v_pk_mul_f32 v[38:39], v[0:1], v[38:39] op_sel_hi:[0,1]
	v_pk_mul_f32 v[36:37], v[0:1], v[36:37] op_sel_hi:[0,1]
	v_pk_mul_f32 v[34:35], v[0:1], v[34:35] op_sel_hi:[0,1]
	v_pk_mul_f32 v[32:33], v[0:1], v[32:33] op_sel_hi:[0,1]
.LBB0_685:
	s_mulk_i32 s71, 0x3400
	s_add_i32 s3, s71, 0
	s_xor_b32 s2, s69, 2
	v_add_u32_e32 v0, s3, v192
	s_mulk_i32 s2, 0x2400
	s_waitcnt vmcnt(5)
	ds_write_b128 v0, v[168:171]
	v_add_u32_e32 v0, s3, v185
	s_waitcnt vmcnt(4)
	ds_write_b128 v0, v[164:167] offset:128
	v_add_u32_e32 v0, s2, v193
	s_add_i32 s2, s67, 6
	s_min_i32 s2, s2, s66
	s_mov_b32 s3, s47
	v_add_u32_e32 v0, 0xd000, v0
	s_lshl_b64 s[4:5], s[2:3], 16
	s_lshl_b64 s[2:3], s[2:3], 12
	s_waitcnt vmcnt(3)
	ds_write2_b64 v0, v[160:161], v[162:163] offset1:2
	v_lshl_add_u64 v[2:3], v[186:187], 0, s[4:5]
	v_lshl_add_u64 v[4:5], v[188:189], 0, s[2:3]
	s_lshl_b64 s[2:3], s[46:47], 7
	global_load_dwordx4 v[168:171], v[2:3], off
	global_load_dwordx4 v[164:167], v[4:5], off
	v_lshl_add_u64 v[2:3], v[190:191], 0, s[2:3]
	global_load_dwordx4 v[160:163], v[2:3], off
	s_add_i32 s46, s67, 2
	s_cmp_ge_i32 s67, s65
	s_cbranch_scc1 .LBB0_696
	s_and_b32 s2, s46, 2
	s_mulk_i32 s2, 0x3400
	v_add_u32_e32 v0, s2, v196
	ds_read_b128 v[2:5], v0
	ds_read_b128 v[6:9], v0 offset:6656
	s_waitcnt lgkmcnt(1)
	v_mfma_f32_32x32x16_bf16 v[112:127], v[2:5], v[128:131], v[48:63]
	ds_read_b128 v[10:13], v0 offset:32
	ds_read_b128 v[202:205], v0 offset:6688
	v_add_f32_e32 v14, 0, v80
	v_add_f32_e32 v14, v81, v14
	v_cvt_pk_bf16_f32 v176, v80, v81
	s_waitcnt lgkmcnt(2)
	v_mfma_f32_32x32x16_bf16 v[96:111], v[6:9], v[128:131], v[48:63]
	v_add_f32_e32 v2, v82, v14
	v_add_f32_e32 v2, v83, v2
	v_add_f32_e32 v14, v84, v2
	v_cvt_pk_bf16_f32 v177, v82, v83
	s_waitcnt lgkmcnt(1)
	v_mfma_f32_32x32x16_bf16 v[112:127], v[10:13], v[132:135], v[112:127]
	ds_read_b128 v[2:5], v0 offset:64
	ds_read_b128 v[6:9], v0 offset:6720
	v_add_f32_e32 v14, v85, v14
	v_add_f32_e32 v14, v86, v14
	v_add_f32_e32 v14, v87, v14
	v_cvt_pk_bf16_f32 v178, v84, v85
	v_cvt_pk_bf16_f32 v179, v86, v87
	s_waitcnt lgkmcnt(2)
	v_mfma_f32_32x32x16_bf16 v[96:111], v[202:205], v[132:135], v[96:111]
	v_add_f32_e32 v10, v88, v14
	v_add_f32_e32 v11, v89, v10
	v_cvt_pk_bf16_f32 v10, v88, v89
	s_waitcnt lgkmcnt(1)
	v_mfma_f32_32x32x16_bf16 v[112:127], v[2:5], v[136:139], v[112:127]
	ds_read_b128 v[80:83], v0 offset:96
	ds_read_b128 v[202:205], v0 offset:6752
	v_add_f32_e32 v11, v90, v11
	v_add_f32_e32 v11, v91, v11
	v_add_f32_e32 v12, v92, v11
	v_cvt_pk_bf16_f32 v11, v90, v91
	s_waitcnt lgkmcnt(2)
	v_mfma_f32_32x32x16_bf16 v[96:111], v[6:9], v[136:139], v[96:111]
	v_add_f32_e32 v2, v93, v12
	v_add_f32_e32 v2, v94, v2
	v_add_f32_e32 v14, v95, v2
	v_cvt_pk_bf16_f32 v12, v92, v93
	v_cvt_pk_bf16_f32 v13, v94, v95
	s_waitcnt lgkmcnt(1)
	v_mfma_f32_32x32x16_bf16 v[112:127], v[80:83], v[140:143], v[112:127]
	ds_read_b128 v[2:5], v0 offset:128
	ds_read_b128 v[206:209], v0 offset:6784
	v_add_f32_e32 v6, v16, v14
	v_add_f32_e32 v7, v17, v6
	v_cvt_pk_bf16_f32 v6, v16, v17
	s_waitcnt lgkmcnt(2)
	v_mfma_f32_32x32x16_bf16 v[96:111], v[202:205], v[140:143], v[96:111]
	v_add_f32_e32 v7, v18, v7
	v_add_f32_e32 v7, v19, v7
	v_add_f32_e32 v8, v20, v7
	v_cvt_pk_bf16_f32 v7, v18, v19
	s_waitcnt lgkmcnt(1)
	v_mfma_f32_32x32x16_bf16 v[112:127], v[2:5], v[144:147], v[112:127]
	ds_read_b128 v[14:17], v0 offset:160
	ds_read_b128 v[80:83], v0 offset:6816
	v_add_f32_e32 v0, v21, v8
	v_add_f32_e32 v0, v22, v0
	v_add_f32_e32 v0, v23, v0
	v_cvt_pk_bf16_f32 v8, v20, v21
	v_cvt_pk_bf16_f32 v9, v22, v23
	s_waitcnt lgkmcnt(2)
	v_mfma_f32_32x32x16_bf16 v[96:111], v[206:209], v[144:147], v[96:111]
	v_add_f32_e32 v0, v24, v0
	v_add_f32_e32 v0, v25, v0
	v_cvt_pk_bf16_f32 v2, v24, v25
	s_waitcnt lgkmcnt(1)
	v_mfma_f32_32x32x16_bf16 v[112:127], v[14:17], v[148:151], v[112:127]
	v_add_f32_e32 v0, v26, v0
	v_add_f32_e32 v0, v27, v0
	v_add_f32_e32 v0, v28, v0
	v_cvt_pk_bf16_f32 v3, v26, v27
	s_waitcnt lgkmcnt(0)
	v_mfma_f32_32x32x16_bf16 v[96:111], v[80:83], v[148:151], v[96:111]
	v_add_f32_e32 v0, v29, v0
	v_add_f32_e32 v0, v30, v0
	v_add_f32_e32 v0, v31, v0
	v_cvt_pk_bf16_f32 v4, v28, v29
	v_cvt_pk_bf16_f32 v5, v30, v31
	s_mul_i32 s4, s69, 0x2400
	v_add_u32_e32 v206, s4, v200
	ds_read_b128 v[16:19], v206 offset:53248
	ds_read_b128 v[202:205], v206 offset:57856
	ds_read_b128 v[210:213], v206 offset:53280
	ds_read_b128 v[214:217], v206 offset:57888
	s_cmp_ge_i32 s70, s65
	v_add_f32_e32 v201, v201, v0
	s_cbranch_scc1 .LBB0_693
	s_cmp_le_i32 s68, s63
	s_cbranch_scc1 .LBB0_691
	v_add_u32_e32 v0, s68, v197
	v_subrev_u32_e32 v15, 31, v0
	v_subrev_u32_e32 v14, 63, v0
	v_cmp_le_i32_e64 s[2:3], v15, v184
	v_cmp_le_i32_e32 vcc, v14, v184
	s_nop 0
	v_cndmask_b32_e64 v96, v194, v96, s[2:3]
	v_cmp_lt_i32_e64 s[2:3], v14, v184
	v_subrev_u32_e32 v14, 30, v0
	v_cmp_le_i32_e64 s[4:5], v14, v184
	v_subrev_u32_e32 v14, 61, v0
	s_nop 0
	v_cndmask_b32_e64 v97, v194, v97, s[4:5]
	v_cmp_le_i32_e64 s[4:5], v14, v184
	v_subrev_u32_e32 v14, 29, v0
	v_cmp_le_i32_e64 s[6:7], v14, v184
	v_subrev_u32_e32 v14, 60, v0
	s_nop 0
	v_cndmask_b32_e64 v98, v194, v98, s[6:7]
	v_cmp_le_i32_e64 s[6:7], v14, v184
	v_subrev_u32_e32 v14, 28, v0
	v_cmp_le_i32_e64 s[8:9], v14, v184
	v_subrev_u32_e32 v14, 55, v0
	s_nop 0
	v_cndmask_b32_e64 v99, v194, v99, s[8:9]
	v_cmp_le_i32_e64 s[8:9], v14, v184
	v_subrev_u32_e32 v14, 23, v0
	v_cmp_le_i32_e64 s[10:11], v14, v184
	v_subrev_u32_e32 v14, 54, v0
	s_nop 0
	v_cndmask_b32_e64 v100, v194, v100, s[10:11]
	v_cmp_le_i32_e64 s[10:11], v14, v184
	v_subrev_u32_e32 v14, 22, v0
	v_cmp_le_i32_e64 s[12:13], v14, v184
	v_subrev_u32_e32 v14, 53, v0
	s_nop 0
	v_cndmask_b32_e64 v101, v194, v101, s[12:13]
	v_cmp_le_i32_e64 s[12:13], v14, v184
	v_subrev_u32_e32 v14, 21, v0
	v_cmp_le_i32_e64 s[14:15], v14, v184
	v_subrev_u32_e32 v14, 52, v0
	s_nop 0
	v_cndmask_b32_e64 v102, v194, v102, s[14:15]
	v_cmp_le_i32_e64 s[14:15], v14, v184
	v_subrev_u32_e32 v14, 20, v0
	v_cmp_le_i32_e64 s[16:17], v14, v184
	v_subrev_u32_e32 v14, 47, v0
	s_nop 0
	v_cndmask_b32_e64 v103, v194, v103, s[16:17]
	v_cmp_le_i32_e64 s[16:17], v14, v184
	v_add_u32_e32 v14, -15, v0
	v_cmp_le_i32_e64 s[18:19], v14, v184
	v_subrev_u32_e32 v14, 46, v0
	s_nop 0
	v_cndmask_b32_e64 v104, v194, v104, s[18:19]
	v_cmp_le_i32_e64 s[18:19], v14, v184
	v_add_u32_e32 v14, -14, v0
	v_cmp_le_i32_e64 s[20:21], v14, v184
	v_subrev_u32_e32 v14, 45, v0
	s_nop 0
	v_cndmask_b32_e64 v105, v194, v105, s[20:21]
	v_cmp_le_i32_e64 s[20:21], v14, v184
	v_add_u32_e32 v14, -13, v0
	v_cmp_le_i32_e64 s[22:23], v14, v184
	v_subrev_u32_e32 v14, 44, v0
	s_nop 0
	v_cndmask_b32_e64 v106, v194, v106, s[22:23]
	v_cmp_le_i32_e64 s[22:23], v14, v184
	v_add_u32_e32 v14, -12, v0
	v_cmp_le_i32_e64 s[24:25], v14, v184
	v_subrev_u32_e32 v14, 39, v0
	s_nop 0
	v_cndmask_b32_e64 v107, v194, v107, s[24:25]
	v_cmp_le_i32_e64 s[24:25], v14, v184
	v_add_u32_e32 v14, -7, v0
	v_cmp_le_i32_e64 s[26:27], v14, v184
	v_subrev_u32_e32 v14, 38, v0
	s_nop 0
	v_cndmask_b32_e64 v108, v194, v108, s[26:27]
	v_cmp_le_i32_e64 s[26:27], v14, v184
	v_add_u32_e32 v14, -6, v0
	v_cmp_le_i32_e64 s[28:29], v14, v184
	v_subrev_u32_e32 v14, 37, v0
	s_nop 0
	v_cndmask_b32_e64 v109, v194, v109, s[28:29]
	v_cmp_le_i32_e64 s[28:29], v14, v184
	v_add_u32_e32 v14, -5, v0
	v_cmp_le_i32_e64 s[30:31], v14, v184
	v_subrev_u32_e32 v14, 36, v0
	v_add_u32_e32 v0, -4, v0
	v_cndmask_b32_e64 v110, v194, v110, s[30:31]
	v_cmp_le_i32_e64 s[30:31], v14, v184
	v_cmp_gt_i32_e64 s[34:35], v0, v184
	s_and_saveexec_b64 s[48:49], s[34:35]
	v_mov_b32_e32 v111, s59
	s_or_b64 exec, exec, s[48:49]
	v_cndmask_b32_e64 v113, v194, v113, s[2:3]
	v_cndmask_b32_e32 v112, v194, v112, vcc
	v_cndmask_b32_e64 v114, v194, v114, s[4:5]
	v_cndmask_b32_e64 v115, v194, v115, s[6:7]
	v_cndmask_b32_e64 v116, v194, v116, s[8:9]
	v_cndmask_b32_e64 v117, v194, v117, s[10:11]
	v_cndmask_b32_e64 v118, v194, v118, s[12:13]
	v_cndmask_b32_e64 v119, v194, v119, s[14:15]
	v_cndmask_b32_e64 v120, v194, v120, s[16:17]
	v_cndmask_b32_e64 v121, v194, v121, s[18:19]
	v_cndmask_b32_e64 v122, v194, v122, s[20:21]
	v_cndmask_b32_e64 v123, v194, v123, s[22:23]
	v_cndmask_b32_e64 v124, v194, v124, s[24:25]
	v_cndmask_b32_e64 v125, v194, v125, s[26:27]
	v_cndmask_b32_e64 v126, v194, v126, s[28:29]
	v_cndmask_b32_e64 v127, v194, v127, s[30:31]
